# nt hint on the 16 final output stores of the last RMSNorm phase (output is never re-read)
# baseline (speedup 1.0000x reference)
; __device__ __forceinline__ float bf_lo(unsigned w) { return __uint_as_float(w << 16); }
; __device__ __forceinline__ float bf_hi(unsigned w) { return __uint_as_float(w & 0xffff0000u); }
; __global__ void __launch_bounds__(NWAVES * 64, 2) hymba_fwd(Args a) {
;     ...
;         for (int it = 0; it < 4; ++it) { const int mb = team_pm * 256 + team_k * 64 + wave * 8 + it * 2;
;             v4u fv[2][4], hv[2][4]; float sf[2], rhi[2];
; #pragma unroll
;             for (int q = 0; q < 2; ++q) { const v4u* fr = (const v4u*)(MIX + (size_t)(mb + q) * DM); const v4u* hr = (const v4u*)(R1 + (size_t)(mb + q) * DM); rhi[q] = ((const float*)(ws + WS_RH))[mb + q];
; #pragma unroll
;                 for (int j = 0; j < 4; ++j) { fv[q][j] = fr[64 * j + lane]; hv[q][j] = hr[64 * j + lane]; } }
; #pragma unroll
;             for (int q = 0; q < 2; ++q) { float t = 0.f;
; #pragma unroll
;                 for (int j = 0; j < 4; ++j)
; #pragma unroll
;                     for (int e = 0; e < 4; ++e) { const float f0 = bf_lo(fv[q][j][e]), f1 = bf_hi(fv[q][j][e]); t += f0 * f0 + f1 * f1; }
;                 sf[q] = t; }
.LBB0_975:
	v_lshl_add_u64 v[38:39], s[94:95], 0, v[0:1]
	v_add_co_u32_e32 v48, vcc, 0xb000000, v38
	s_add_u32 s2, s94, s4
	s_nop 0
	v_addc_co_u32_e32 v49, vcc, 0, v39, vcc
	v_add_co_u32_e32 v54, vcc, 0x7000000, v38
	s_addc_u32 s3, s95, s5
	s_nop 0
	v_addc_co_u32_e32 v55, vcc, 0, v39, vcc
	global_load_dwordx2 v[44:45], v126, s[2:3]
	global_load_dwordx4 v[50:53], v[48:49], off
	global_load_dwordx4 v[58:61], v[48:49], off offset:1024
	global_load_dwordx4 v[64:67], v[48:49], off offset:2048
	v_add_co_u32_e32 v56, vcc, s11, v38
	global_load_dwordx4 v[74:77], v[48:49], off offset:3072
	global_load_dwordx4 v[78:81], v[54:55], off
	global_load_dwordx4 v[82:85], v[54:55], off offset:1024
	global_load_dwordx4 v[90:93], v[54:55], off offset:2048
	v_addc_co_u32_e32 v57, vcc, 0, v39, vcc
	global_load_dwordx4 v[98:101], v[54:55], off offset:3072
	global_load_dwordx4 v[112:115], v[56:57], off
	global_load_dwordx4 v[120:123], v[56:57], off offset:1024
	global_load_dwordx4 v[130:133], v[56:57], off offset:2048
	v_add_co_u32_e32 v38, vcc, s12, v38
	v_lshl_add_u64 v[36:37], v[34:35], 0, s[6:7]
	s_nop 0
	v_addc_co_u32_e32 v39, vcc, 0, v39, vcc
	global_load_dwordx4 v[134:137], v[38:39], off offset:1024
	global_load_dwordx4 v[138:141], v[38:39], off offset:2048
	global_load_dwordx4 v[142:145], v[38:39], off
	global_load_dwordx4 v[154:157], v[56:57], off offset:3072
	global_load_dwordx4 v[158:161], v[38:39], off offset:3072
	v_add_co_u32_e64 v46, s[0:1], s10, v36
	s_add_u32 s6, s6, 0x4000
	s_nop 0
	v_addc_co_u32_e64 v47, s[0:1], 0, v37, s[0:1]
	v_add_co_u32_e64 v42, s[0:1], s14, v36
	s_addc_u32 s7, s7, 0
	s_nop 0
	v_addc_co_u32_e64 v43, s[0:1], 0, v37, s[0:1]
	v_add_co_u32_e64 v40, s[0:1], s15, v36
	s_add_u32 s4, s4, 8
	s_nop 0
	v_addc_co_u32_e64 v41, s[0:1], 0, v37, s[0:1]
	s_addc_u32 s5, s5, 0
	v_lshl_add_u64 v[0:1], v[0:1], 0, s[8:9]
	s_cmp_eq_u32 s6, 0x10000
	s_waitcnt vmcnt(15)
	v_and_b32_e32 v39, 0xffff0000, v50
	v_and_b32_e32 v49, 0xffff0000, v51
	v_lshlrev_b32_e32 v38, 16, v50
	v_lshlrev_b32_e32 v48, 16, v51
	v_and_b32_e32 v51, 0xffff0000, v52
	v_mul_f32_e32 v129, v39, v39
	v_mul_f32_e32 v153, v49, v49
	v_lshlrev_b32_e32 v50, 16, v52
	v_lshlrev_b32_e32 v52, 16, v53
	v_and_b32_e32 v53, 0xffff0000, v53
	v_mul_f32_e32 v173, v51, v51
	v_fmac_f32_e32 v129, v38, v38
	v_fmac_f32_e32 v153, v48, v48
	s_waitcnt vmcnt(14)
	v_and_b32_e32 v55, 0xffff0000, v58
	v_mul_f32_e32 v192, v53, v53
	v_fmac_f32_e32 v173, v50, v50
	s_waitcnt vmcnt(7)
	v_and_b32_e32 v109, 0xffff0000, v112
	v_and_b32_e32 v111, 0xffff0000, v113
	v_add_f32_e32 v129, v129, v153
	v_lshlrev_b32_e32 v54, 16, v58
	v_and_b32_e32 v57, 0xffff0000, v59
	v_mul_f32_e32 v193, v55, v55
	v_fmac_f32_e32 v192, v52, v52
	v_lshlrev_b32_e32 v108, 16, v112
	v_lshlrev_b32_e32 v110, 16, v113
	v_and_b32_e32 v113, 0xffff0000, v114
	v_mul_f32_e32 v153, v109, v109
	v_mul_f32_e32 v203, v111, v111
	v_add_f32_e32 v129, v129, v173
	v_lshlrev_b32_e32 v56, 16, v59
	v_and_b32_e32 v59, 0xffff0000, v60
	v_mul_f32_e32 v194, v57, v57
	v_fmac_f32_e32 v193, v54, v54
	v_lshlrev_b32_e32 v112, 16, v114
	v_lshlrev_b32_e32 v114, 16, v115
	v_and_b32_e32 v115, 0xffff0000, v115
	v_mul_f32_e32 v204, v113, v113
	v_fmac_f32_e32 v153, v108, v108
	v_fmac_f32_e32 v203, v110, v110
	v_add_f32_e32 v129, v129, v192
	v_lshlrev_b32_e32 v58, 16, v60
	v_lshlrev_b32_e32 v60, 16, v61
	v_and_b32_e32 v61, 0xffff0000, v61
	v_mul_f32_e32 v195, v59, v59
	v_fmac_f32_e32 v194, v56, v56
	s_waitcnt vmcnt(6)
	v_and_b32_e32 v117, 0xffff0000, v120
	v_mul_f32_e32 v205, v115, v115
	v_fmac_f32_e32 v204, v112, v112
	v_add_f32_e32 v153, v153, v203
	v_add_f32_e32 v129, v129, v193
	v_and_b32_e32 v63, 0xffff0000, v64
	v_mul_f32_e32 v196, v61, v61
	v_fmac_f32_e32 v195, v58, v58
	v_lshlrev_b32_e32 v116, 16, v120
	v_and_b32_e32 v119, 0xffff0000, v121
	v_mul_f32_e32 v206, v117, v117
	v_fmac_f32_e32 v205, v114, v114
	v_add_f32_e32 v153, v153, v204
	v_add_f32_e32 v129, v129, v194
	v_lshlrev_b32_e32 v62, 16, v64
	v_lshlrev_b32_e32 v64, 16, v65
	v_and_b32_e32 v65, 0xffff0000, v65
	v_mul_f32_e32 v197, v63, v63
	v_fmac_f32_e32 v196, v60, v60
	v_lshlrev_b32_e32 v118, 16, v121
	v_and_b32_e32 v121, 0xffff0000, v122
	v_mul_f32_e32 v207, v119, v119
	v_fmac_f32_e32 v206, v116, v116
	v_add_f32_e32 v153, v153, v205
	v_add_f32_e32 v129, v129, v195
	v_and_b32_e32 v69, 0xffff0000, v66
	v_mul_f32_e32 v198, v65, v65
	v_fmac_f32_e32 v197, v62, v62
	v_lshlrev_b32_e32 v120, 16, v122
	v_lshlrev_b32_e32 v122, 16, v123
	v_and_b32_e32 v123, 0xffff0000, v123
	v_mul_f32_e32 v208, v121, v121
	v_fmac_f32_e32 v207, v118, v118
	v_add_f32_e32 v153, v153, v206
	v_add_f32_e32 v129, v129, v196
	v_lshlrev_b32_e32 v68, 16, v66
	v_and_b32_e32 v73, 0xffff0000, v67
	v_mul_f32_e32 v199, v69, v69
	v_fmac_f32_e32 v198, v64, v64
	s_waitcnt vmcnt(5)
	v_and_b32_e32 v125, 0xffff0000, v130
	v_mul_f32_e32 v209, v123, v123
	v_fmac_f32_e32 v208, v120, v120
	v_add_f32_e32 v153, v153, v207
	v_add_f32_e32 v129, v129, v197
	v_lshlrev_b32_e32 v72, 16, v67
	v_mul_f32_e32 v200, v73, v73
	v_and_b32_e32 v103, 0xffff0000, v74
	v_fmac_f32_e32 v199, v68, v68
	v_lshlrev_b32_e32 v124, 16, v130
	v_lshlrev_b32_e32 v130, 16, v131
	v_and_b32_e32 v131, 0xffff0000, v131
	v_mul_f32_e32 v210, v125, v125
	v_fmac_f32_e32 v209, v122, v122
	v_add_f32_e32 v153, v153, v208
	v_add_f32_e32 v129, v129, v198
	v_lshlrev_b32_e32 v102, 16, v74
	v_and_b32_e32 v105, 0xffff0000, v75
	v_and_b32_e32 v107, 0xffff0000, v77
	v_and_b32_e32 v106, 0xffff0000, v76
	v_fmac_f32_e32 v200, v72, v72
	v_mul_f32_e32 v201, v103, v103
	v_and_b32_e32 v165, 0xffff0000, v132
	v_mul_f32_e32 v211, v131, v131
	v_fmac_f32_e32 v210, v124, v124
	v_add_f32_e32 v153, v153, v209
	v_add_f32_e32 v129, v129, v199
	v_lshlrev_b32_e32 v104, 16, v75
	v_lshlrev_b32_e32 v147, 16, v77
	v_lshlrev_b32_e32 v146, 16, v76
	v_mul_f32_e32 v202, v105, v105
	v_pk_mul_f32 v[162:163], v[106:107], v[106:107]
	v_lshlrev_b32_e32 v164, 16, v132
	v_lshlrev_b32_e32 v132, 16, v133
	v_and_b32_e32 v133, 0xffff0000, v133
	v_fmac_f32_e32 v201, v102, v102
	v_mul_f32_e32 v212, v165, v165
	v_fmac_f32_e32 v211, v130, v130
	v_add_f32_e32 v153, v153, v210
	v_add_f32_e32 v129, v129, v200
	v_mov_b32_e32 v166, v146
	v_mov_b32_e32 v167, v106
	v_mov_b32_e32 v106, v147
	v_fmac_f32_e32 v202, v104, v104
	v_pk_fma_f32 v[146:147], v[146:147], v[146:147], v[162:163]
	v_mul_f32_e32 v213, v133, v133
	s_waitcnt vmcnt(1)
; __device__ __forceinline__ float bf_lo(unsigned w) { return __uint_as_float(w << 16); }
; __device__ __forceinline__ float bf_hi(unsigned w) { return __uint_as_float(w & 0xffff0000u); }
; __device__ __forceinline__ float wave_sum(float v) {
; #pragma unroll
;     for (int o = 1; o < 64; o <<= 1) v += __shfl_xor(v, o);
;     return v;
; __global__ void __launch_bounds__(NWAVES * 64, 2) hymba_fwd(Args a) {
;     ...
;             for (int q = 0; q < 2; ++q) { float t = 0.f;
; #pragma unroll
;                 for (int j = 0; j < 4; ++j)
; #pragma unroll
;                     for (int e = 0; e < 4; ++e) { const float f0 = bf_lo(fv[q][j][e]), f1 = bf_hi(fv[q][j][e]); t += f0 * f0 + f1 * f1; }
;                 sf[q] = t; }
; #pragma unroll
;             for (int q = 0; q < 2; ++q) {
;                 const float rf = 1.0f / sqrtf(wave_sum(sf[q]) * (1.0f / DM) + RMS_EPS), rx = rhi[q]; f32x4* ho = (f32x4*)(a.out + (size_t)(mb + q) * DM);
	v_and_b32_e32 v163, 0xffff0000, v154
	v_fmac_f32_e32 v212, v164, v164
	v_add_f32_e32 v153, v153, v211
	v_add_f32_e32 v129, v129, v201
	v_lshlrev_b32_e32 v162, 16, v154
	v_lshlrev_b32_e32 v154, 16, v155
	v_and_b32_e32 v155, 0xffff0000, v155
	v_fmac_f32_e32 v213, v132, v132
	v_mul_f32_e32 v173, v163, v163
	v_add_f32_e32 v153, v153, v212
	v_add_f32_e32 v129, v129, v202
	v_lshlrev_b32_e32 v169, 16, v157
	v_lshlrev_b32_e32 v168, 16, v156
	v_and_b32_e32 v157, 0xffff0000, v157
	v_and_b32_e32 v156, 0xffff0000, v156
	v_mul_f32_e32 v214, v155, v155
	v_fmac_f32_e32 v173, v162, v162
	v_add_f32_e32 v153, v153, v213
	v_add_f32_e32 v129, v129, v146
	v_pk_mul_f32 v[188:189], v[156:157], v[156:157]
	v_fmac_f32_e32 v214, v154, v154
	v_add_f32_e32 v146, v153, v173
	v_add_f32_e32 v129, v129, v147
	v_mov_b32_e32 v190, v168
	v_mov_b32_e32 v191, v156
	v_mov_b32_e32 v156, v169
	v_pk_fma_f32 v[168:169], v[168:169], v[168:169], v[188:189]
	v_add_f32_e32 v146, v146, v214
	ds_bpermute_b32 v147, v148, v129
	v_add_f32_e32 v146, v146, v168
	v_add_f32_e32 v146, v146, v169
	ds_bpermute_b32 v153, v148, v146
	v_lshlrev_b32_e32 v66, 16, v78
	s_waitcnt lgkmcnt(1)
	v_add_f32_e32 v129, v129, v147
	ds_bpermute_b32 v147, v149, v129
	v_and_b32_e32 v67, 0xffff0000, v78
	s_waitcnt lgkmcnt(1)
	v_add_f32_e32 v146, v146, v153
	ds_bpermute_b32 v153, v149, v146
	v_lshlrev_b32_e32 v70, 16, v79
	s_waitcnt lgkmcnt(1)
	v_add_f32_e32 v129, v129, v147
	ds_bpermute_b32 v147, v150, v129
	v_and_b32_e32 v71, 0xffff0000, v79
	s_waitcnt lgkmcnt(1)
	v_add_f32_e32 v146, v146, v153
	ds_bpermute_b32 v153, v150, v146
	v_lshlrev_b32_e32 v74, 16, v80
	s_waitcnt lgkmcnt(1)
	v_add_f32_e32 v129, v129, v147
	ds_bpermute_b32 v147, v151, v129
	v_and_b32_e32 v75, 0xffff0000, v80
	s_waitcnt lgkmcnt(1)
	v_add_f32_e32 v146, v146, v153
	ds_bpermute_b32 v153, v151, v146
	v_lshlrev_b32_e32 v76, 16, v81
	s_waitcnt lgkmcnt(1)
	v_add_f32_e32 v129, v129, v147
	ds_bpermute_b32 v147, v152, v129
	v_and_b32_e32 v77, 0xffff0000, v81
	s_waitcnt lgkmcnt(1)
	v_add_f32_e32 v146, v146, v153
	ds_bpermute_b32 v153, v152, v146
	v_lshlrev_b32_e32 v80, 16, v83
	s_waitcnt lgkmcnt(1)
	v_add_f32_e32 v129, v129, v147
	ds_bpermute_b32 v147, v172, v129
	v_and_b32_e32 v81, 0xffff0000, v83
	s_waitcnt lgkmcnt(1)
	v_add_f32_e32 v146, v146, v153
	ds_bpermute_b32 v153, v172, v146
	v_lshlrev_b32_e32 v78, 16, v82
	s_waitcnt lgkmcnt(1)
	v_add_f32_e32 v129, v129, v147
	v_fmamk_f32 v129, v129, 0x3a000000, v127
	v_mul_f32_e32 v147, 0x4f800000, v129
	v_cmp_gt_f32_e32 vcc, s13, v129
	s_waitcnt lgkmcnt(0)
	v_add_f32_e32 v146, v146, v153
	v_fmamk_f32 v146, v146, 0x3a000000, v127
	v_cndmask_b32_e32 v129, v129, v147, vcc
	v_sqrt_f32_e32 v147, v129
	v_mul_f32_e32 v153, 0x4f800000, v146
	v_cmp_gt_f32_e64 s[0:1], s13, v146
	v_and_b32_e32 v79, 0xffff0000, v82
	v_add_u32_e32 v168, -1, v147
	v_cndmask_b32_e64 v146, v146, v153, s[0:1]
	v_sqrt_f32_e32 v153, v146
	v_add_u32_e32 v169, 1, v147
	v_fma_f32 v173, -v168, v147, v129
	v_fma_f32 v188, -v169, v147, v129
	v_cmp_ge_f32_e64 s[2:3], 0, v173
	v_add_u32_e32 v173, 1, v153
	v_lshlrev_b32_e32 v82, 16, v84
	v_cndmask_b32_e64 v147, v147, v168, s[2:3]
	v_add_u32_e32 v168, -1, v153
	v_cmp_lt_f32_e64 s[2:3], 0, v188
	v_fma_f32 v188, -v173, v153, v146
	v_and_b32_e32 v83, 0xffff0000, v84
	v_cndmask_b32_e64 v147, v147, v169, s[2:3]
	v_fma_f32 v169, -v168, v153, v146
	v_cmp_ge_f32_e64 s[2:3], 0, v169
	v_mul_f32_e32 v189, 0x37800000, v147
	v_cndmask_b32_e32 v147, v147, v189, vcc
	v_cndmask_b32_e64 v153, v153, v168, s[2:3]
	v_cmp_lt_f32_e64 s[2:3], 0, v188
	v_cmp_class_f32_e32 vcc, v129, v128
	v_lshlrev_b32_e32 v84, 16, v85
	v_cndmask_b32_e64 v153, v153, v173, s[2:3]
	v_cndmask_b32_e32 v129, v147, v129, vcc
	v_mul_f32_e32 v147, 0x37800000, v153
	v_div_scale_f32 v168, s[2:3], v129, v129, 1.0
	v_cndmask_b32_e64 v147, v153, v147, s[0:1]
	v_cmp_class_f32_e64 s[0:1], v146, v128
	v_rcp_f32_e32 v153, v168
	v_div_scale_f32 v169, vcc, 1.0, v129, 1.0
	v_cndmask_b32_e64 v173, v147, v146, s[0:1]
	v_div_scale_f32 v147, s[0:1], v173, v173, 1.0
	v_rcp_f32_e32 v189, v147
	v_fma_f32 v146, -v168, v153, 1.0
	v_fmac_f32_e32 v153, v146, v153
	v_mul_f32_e32 v146, v169, v153
	v_fma_f32 v192, -v147, v189, 1.0
	v_div_scale_f32 v188, s[0:1], 1.0, v173, 1.0
	v_fma_f32 v193, -v168, v146, v169
	v_fmac_f32_e32 v189, v192, v189
	v_fmac_f32_e32 v146, v193, v153
	v_mul_f32_e32 v192, v188, v189
	v_fma_f32 v168, -v168, v146, v169
	v_fma_f32 v169, -v147, v192, v188
	v_div_fmas_f32 v146, v168, v153, v146
	v_fmac_f32_e32 v192, v169, v189
	v_div_fixup_f32 v146, v146, v129, 1.0
	v_fma_f32 v129, -v147, v192, v188
	s_mov_b64 vcc, s[0:1]
	v_pk_mul_f32 v[38:39], v[146:147], v[38:39] op_sel_hi:[0,1]
	v_pk_mul_f32 v[48:49], v[146:147], v[48:49] op_sel_hi:[0,1]
	v_pk_mul_f32 v[56:57], v[146:147], v[56:57] op_sel_hi:[0,1]
	v_div_fmas_f32 v129, v129, v189, v192
	v_pk_mul_f32 v[50:51], v[146:147], v[50:51] op_sel_hi:[0,1]
	v_pk_mul_f32 v[52:53], v[146:147], v[52:53] op_sel_hi:[0,1]
	v_pk_mul_f32 v[54:55], v[146:147], v[54:55] op_sel_hi:[0,1]
	v_pk_mul_f32 v[58:59], v[146:147], v[58:59] op_sel_hi:[0,1]
	v_pk_mul_f32 v[60:61], v[146:147], v[60:61] op_sel_hi:[0,1]
	v_pk_mul_f32 v[62:63], v[146:147], v[62:63] op_sel_hi:[0,1]
	v_pk_mul_f32 v[64:65], v[146:147], v[64:65] op_sel_hi:[0,1]
	v_pk_mul_f32 v[68:69], v[146:147], v[68:69] op_sel_hi:[0,1]
	v_pk_mul_f32 v[72:73], v[146:147], v[72:73] op_sel_hi:[0,1]
	v_pk_mul_f32 v[102:103], v[146:147], v[102:103] op_sel_hi:[0,1]
	v_pk_mul_f32 v[104:105], v[146:147], v[104:105] op_sel_hi:[0,1]
	v_pk_mul_f32 v[166:167], v[146:147], v[166:167] op_sel_hi:[0,1]
	v_pk_mul_f32 v[106:107], v[146:147], v[106:107] op_sel_hi:[0,1]
; __device__ __forceinline__ float bf_lo(unsigned w) { return __uint_as_float(w << 16); }
; __device__ __forceinline__ float bf_hi(unsigned w) { return __uint_as_float(w & 0xffff0000u); }
; __global__ void __launch_bounds__(NWAVES * 64, 2) hymba_fwd(Args a) {
;     ...
;             for (int q = 0; q < 2; ++q) {
;                 const float rf = 1.0f / sqrtf(wave_sum(sf[q]) * (1.0f / DM) + RMS_EPS), rx = rhi[q]; f32x4* ho = (f32x4*)(a.out + (size_t)(mb + q) * DM);
; #pragma unroll
;                 for (int j = 0; j < 4; ++j) {
;                     const f32x4 g0 = gq[2 * j], g1 = gq[2 * j + 1]; const v4u fj = fv[q][j], hj = hv[q][j]; f32x4 h0, h1;
;                     h0.x = bf_lo(hj.x) * rx + bf_lo(fj.x) * rf * g0.x; h0.y = bf_hi(hj.x) * rx + bf_hi(fj.x) * rf * g0.y; h0.z = bf_lo(hj.y) * rx + bf_lo(fj.y) * rf * g0.z; h0.w = bf_hi(hj.y) * rx + bf_hi(fj.y) * rf * g0.w;
;                     h1.x = bf_lo(hj.z) * rx + bf_lo(fj.z) * rf * g1.x; h1.y = bf_hi(hj.z) * rx + bf_hi(fj.z) * rf * g1.y; h1.z = bf_lo(hj.w) * rx + bf_lo(fj.w) * rf * g1.z; h1.w = bf_hi(hj.w) * rx + bf_hi(fj.w) * rf * g1.w;
;                     ho[128 * j + 2 * lane] = h0; ho[128 * j + 2 * lane + 1] = h1;
;                 }
	v_pk_mul_f32 v[38:39], v[2:3], v[38:39]
	v_pk_mul_f32 v[146:147], v[4:5], v[48:49]
	v_pk_mul_f32 v[194:195], v[12:13], v[56:57]
	v_div_fixup_f32 v204, v129, v173, 1.0
	v_and_b32_e32 v85, 0xffff0000, v85
	v_lshlrev_b32_e32 v86, 16, v90
	v_and_b32_e32 v87, 0xffff0000, v90
	v_lshlrev_b32_e32 v88, 16, v91
	v_and_b32_e32 v89, 0xffff0000, v91
	v_lshlrev_b32_e32 v90, 16, v92
	v_and_b32_e32 v91, 0xffff0000, v92
	v_lshlrev_b32_e32 v92, 16, v93
	v_and_b32_e32 v93, 0xffff0000, v93
	v_lshlrev_b32_e32 v94, 16, v98
	v_and_b32_e32 v95, 0xffff0000, v98
	v_lshlrev_b32_e32 v96, 16, v99
	v_and_b32_e32 v97, 0xffff0000, v99
	v_lshlrev_b32_e32 v98, 16, v100
	v_and_b32_e32 v99, 0xffff0000, v100
	v_lshlrev_b32_e32 v100, 16, v101
	v_and_b32_e32 v101, 0xffff0000, v101
	v_pk_mul_f32 v[168:169], v[6:7], v[50:51]
	v_pk_mul_f32 v[188:189], v[8:9], v[52:53]
	v_pk_mul_f32 v[192:193], v[10:11], v[54:55]
	v_pk_mul_f32 v[196:197], v[14:15], v[58:59]
	v_pk_mul_f32 v[198:199], v[16:17], v[60:61]
	v_pk_mul_f32 v[200:201], v[18:19], v[62:63]
	v_pk_mul_f32 v[202:203], v[20:21], v[64:65]
	v_pk_mul_f32 v[68:69], v[22:23], v[68:69]
	v_pk_mul_f32 v[72:73], v[24:25], v[72:73]
	v_pk_mul_f32 v[102:103], v[26:27], v[102:103]
	v_pk_mul_f32 v[104:105], v[28:29], v[104:105]
	v_pk_mul_f32 v[166:167], v[30:31], v[166:167]
	v_pk_mul_f32 v[106:107], v[32:33], v[106:107]
	v_pk_fma_f32 v[48:49], v[44:45], v[66:67], v[38:39] op_sel_hi:[0,1,1]
	v_pk_fma_f32 v[50:51], v[44:45], v[70:71], v[146:147] op_sel_hi:[0,1,1]
	v_pk_fma_f32 v[58:59], v[44:45], v[80:81], v[194:195] op_sel_hi:[0,1,1]
	v_pk_mul_f32 v[38:39], v[204:205], v[108:109] op_sel_hi:[0,1]
	v_pk_mul_f32 v[80:81], v[204:205], v[110:111] op_sel_hi:[0,1]
	v_lshlrev_b32_e32 v170, 16, v142
	v_and_b32_e32 v171, 0xffff0000, v142
	v_lshlrev_b32_e32 v142, 16, v143
	v_and_b32_e32 v143, 0xffff0000, v143
	v_pk_fma_f32 v[52:53], v[44:45], v[74:75], v[168:169] op_sel_hi:[0,1,1]
	v_pk_fma_f32 v[54:55], v[44:45], v[76:77], v[188:189] op_sel_hi:[0,1,1]
	v_pk_fma_f32 v[56:57], v[44:45], v[78:79], v[192:193] op_sel_hi:[0,1,1]
	v_pk_fma_f32 v[60:61], v[44:45], v[82:83], v[196:197] op_sel_hi:[0,1,1]
	v_pk_fma_f32 v[62:63], v[44:45], v[84:85], v[198:199] op_sel_hi:[0,1,1]
	v_pk_fma_f32 v[64:65], v[44:45], v[86:87], v[200:201] op_sel_hi:[0,1,1]
	v_pk_fma_f32 v[66:67], v[44:45], v[88:89], v[202:203] op_sel_hi:[0,1,1]
	v_pk_fma_f32 v[68:69], v[44:45], v[90:91], v[68:69] op_sel_hi:[0,1,1]
	v_pk_fma_f32 v[70:71], v[44:45], v[92:93], v[72:73] op_sel_hi:[0,1,1]
	v_pk_fma_f32 v[72:73], v[44:45], v[94:95], v[102:103] op_sel_hi:[0,1,1]
	v_pk_fma_f32 v[74:75], v[44:45], v[96:97], v[104:105] op_sel_hi:[0,1,1]
	v_pk_fma_f32 v[76:77], v[44:45], v[98:99], v[166:167] op_sel_hi:[0,1,1]
	v_pk_fma_f32 v[78:79], v[44:45], v[100:101], v[106:107] op_sel_hi:[0,1,1]
	v_pk_mul_f32 v[82:83], v[204:205], v[112:113] op_sel_hi:[0,1]
	v_pk_mul_f32 v[84:85], v[204:205], v[114:115] op_sel_hi:[0,1]
	v_pk_mul_f32 v[86:87], v[204:205], v[116:117] op_sel_hi:[0,1]
	v_pk_mul_f32 v[88:89], v[204:205], v[118:119] op_sel_hi:[0,1]
	v_pk_mul_f32 v[90:91], v[204:205], v[120:121] op_sel_hi:[0,1]
	v_pk_mul_f32 v[92:93], v[204:205], v[122:123] op_sel_hi:[0,1]
	v_pk_mul_f32 v[94:95], v[204:205], v[124:125] op_sel_hi:[0,1]
	v_pk_mul_f32 v[96:97], v[204:205], v[130:131] op_sel_hi:[0,1]
	v_pk_mul_f32 v[98:99], v[204:205], v[164:165] op_sel_hi:[0,1]
	v_pk_mul_f32 v[100:101], v[204:205], v[132:133] op_sel_hi:[0,1]
	v_pk_mul_f32 v[102:103], v[204:205], v[162:163] op_sel_hi:[0,1]
	v_pk_mul_f32 v[104:105], v[204:205], v[154:155] op_sel_hi:[0,1]
	v_pk_mul_f32 v[106:107], v[204:205], v[190:191] op_sel_hi:[0,1]
	v_pk_mul_f32 v[108:109], v[204:205], v[156:157] op_sel_hi:[0,1]
	global_store_dwordx4 v[36:37], v[48:51], off nt
	global_store_dwordx4 v[36:37], v[52:55], off offset:16 nt
	global_store_dwordx4 v[36:37], v[56:59], off offset:2048 nt
	global_store_dwordx4 v[36:37], v[60:63], off offset:2064 nt
	global_store_dwordx4 v[42:43], v[64:67], off offset:-4096 nt
	global_store_dwordx4 v[46:47], v[68:71], off offset:16 nt
	global_store_dwordx4 v[46:47], v[72:75], off offset:2048 nt
	global_store_dwordx4 v[46:47], v[76:79], off offset:2064 nt
	v_pk_mul_f32 v[36:37], v[2:3], v[38:39]
	v_pk_mul_f32 v[38:39], v[4:5], v[80:81]
	v_lshlrev_b32_e32 v174, 16, v144
	v_and_b32_e32 v175, 0xffff0000, v144
	v_lshlrev_b32_e32 v144, 16, v145
	v_and_b32_e32 v145, 0xffff0000, v145
	v_lshlrev_b32_e32 v176, 16, v134
	v_and_b32_e32 v177, 0xffff0000, v134
	v_lshlrev_b32_e32 v134, 16, v135
	v_and_b32_e32 v135, 0xffff0000, v135
	v_lshlrev_b32_e32 v178, 16, v136
	v_and_b32_e32 v179, 0xffff0000, v136
	v_lshlrev_b32_e32 v136, 16, v137
	v_and_b32_e32 v137, 0xffff0000, v137
	v_lshlrev_b32_e32 v180, 16, v138
	v_and_b32_e32 v181, 0xffff0000, v138
	v_lshlrev_b32_e32 v138, 16, v139
	v_and_b32_e32 v139, 0xffff0000, v139
	v_lshlrev_b32_e32 v182, 16, v140
	v_and_b32_e32 v183, 0xffff0000, v140
	v_lshlrev_b32_e32 v140, 16, v141
	v_and_b32_e32 v141, 0xffff0000, v141
	s_waitcnt vmcnt(8)
; __device__ __forceinline__ float bf_lo(unsigned w) { return __uint_as_float(w << 16); }
; __device__ __forceinline__ float bf_hi(unsigned w) { return __uint_as_float(w & 0xffff0000u); }
; __global__ void __launch_bounds__(NWAVES * 64, 2) hymba_fwd(Args a) {
;     ...
;             for (int q = 0; q < 2; ++q) {
;                 const float rf = 1.0f / sqrtf(wave_sum(sf[q]) * (1.0f / DM) + RMS_EPS), rx = rhi[q]; f32x4* ho = (f32x4*)(a.out + (size_t)(mb + q) * DM);
; #pragma unroll
;                 for (int j = 0; j < 4; ++j) {
;                     const f32x4 g0 = gq[2 * j], g1 = gq[2 * j + 1]; const v4u fj = fv[q][j], hj = hv[q][j]; f32x4 h0, h1;
;                     h0.x = bf_lo(hj.x) * rx + bf_lo(fj.x) * rf * g0.x; h0.y = bf_hi(hj.x) * rx + bf_hi(fj.x) * rf * g0.y; h0.z = bf_lo(hj.y) * rx + bf_lo(fj.y) * rf * g0.z; h0.w = bf_hi(hj.y) * rx + bf_hi(fj.y) * rf * g0.w;
;                     h1.x = bf_lo(hj.z) * rx + bf_lo(fj.z) * rf * g1.x; h1.y = bf_hi(hj.z) * rx + bf_hi(fj.z) * rf * g1.y; h1.z = bf_lo(hj.w) * rx + bf_lo(fj.w) * rf * g1.z; h1.w = bf_hi(hj.w) * rx + bf_hi(fj.w) * rf * g1.w;
;                     ho[128 * j + 2 * lane] = h0; ho[128 * j + 2 * lane + 1] = h1;
;                 }
	v_lshlrev_b32_e32 v184, 16, v158
	v_and_b32_e32 v185, 0xffff0000, v158
	v_lshlrev_b32_e32 v158, 16, v159
	v_and_b32_e32 v159, 0xffff0000, v159
	v_lshlrev_b32_e32 v186, 16, v160
	v_and_b32_e32 v187, 0xffff0000, v160
	v_lshlrev_b32_e32 v160, 16, v161
	v_and_b32_e32 v161, 0xffff0000, v161
	v_pk_mul_f32 v[46:47], v[6:7], v[82:83]
	v_pk_mul_f32 v[48:49], v[8:9], v[84:85]
	v_pk_mul_f32 v[50:51], v[10:11], v[86:87]
	v_pk_mul_f32 v[52:53], v[12:13], v[88:89]
	v_pk_mul_f32 v[54:55], v[14:15], v[90:91]
	v_pk_mul_f32 v[56:57], v[16:17], v[92:93]
	v_pk_mul_f32 v[58:59], v[18:19], v[94:95]
	v_pk_mul_f32 v[60:61], v[20:21], v[96:97]
	v_pk_mul_f32 v[62:63], v[22:23], v[98:99]
	v_pk_mul_f32 v[64:65], v[24:25], v[100:101]
	v_pk_mul_f32 v[66:67], v[26:27], v[102:103]
	v_pk_mul_f32 v[68:69], v[28:29], v[104:105]
	v_pk_mul_f32 v[70:71], v[30:31], v[106:107]
	v_pk_mul_f32 v[72:73], v[32:33], v[108:109]
	v_pk_fma_f32 v[36:37], v[44:45], v[170:171], v[36:37] op_sel:[1,0,0]
	v_pk_fma_f32 v[38:39], v[44:45], v[142:143], v[38:39] op_sel:[1,0,0]
	v_pk_fma_f32 v[46:47], v[44:45], v[174:175], v[46:47] op_sel:[1,0,0]
	v_pk_fma_f32 v[48:49], v[44:45], v[144:145], v[48:49] op_sel:[1,0,0]
	v_pk_fma_f32 v[50:51], v[44:45], v[176:177], v[50:51] op_sel:[1,0,0]
	v_pk_fma_f32 v[52:53], v[44:45], v[134:135], v[52:53] op_sel:[1,0,0]
	v_pk_fma_f32 v[54:55], v[44:45], v[178:179], v[54:55] op_sel:[1,0,0]
	v_pk_fma_f32 v[56:57], v[44:45], v[136:137], v[56:57] op_sel:[1,0,0]
	v_pk_fma_f32 v[58:59], v[44:45], v[180:181], v[58:59] op_sel:[1,0,0]
	v_pk_fma_f32 v[60:61], v[44:45], v[138:139], v[60:61] op_sel:[1,0,0]
	v_pk_fma_f32 v[62:63], v[44:45], v[182:183], v[62:63] op_sel:[1,0,0]
	v_pk_fma_f32 v[64:65], v[44:45], v[140:141], v[64:65] op_sel:[1,0,0]
	v_pk_fma_f32 v[66:67], v[44:45], v[184:185], v[66:67] op_sel:[1,0,0]
	v_pk_fma_f32 v[68:69], v[44:45], v[158:159], v[68:69] op_sel:[1,0,0]
	v_pk_fma_f32 v[70:71], v[44:45], v[186:187], v[70:71] op_sel:[1,0,0]
	v_pk_fma_f32 v[72:73], v[44:45], v[160:161], v[72:73] op_sel:[1,0,0]
	global_store_dwordx4 v[42:43], v[36:39], off nt
	global_store_dwordx4 v[42:43], v[46:49], off offset:16 nt
	global_store_dwordx4 v[42:43], v[50:53], off offset:2048 nt
	global_store_dwordx4 v[42:43], v[54:57], off offset:2064 nt
	global_store_dwordx4 v[40:41], v[58:61], off nt
	global_store_dwordx4 v[40:41], v[62:65], off offset:16 nt
	global_store_dwordx4 v[40:41], v[66:69], off offset:2048 nt
	global_store_dwordx4 v[40:41], v[70:73], off offset:2064 nt
	s_cbranch_scc0 .LBB0_975
	s_endpgm
